# NSA top-k rank loop: LDS read of the next candidate prefetched one iteration ahead (free VGPR)
# speedup vs baseline: 1.0019x; 1.0019x over previous
; DI void nsa_item(const bf16_t* __restrict__ P, const bf16_t* __restrict__ KC, const bf16_t* __restrict__ VCT,
;                  const bf16_t* __restrict__ VTS, const bf16_t* __restrict__ VTW, bf16_t* __restrict__ Y, int item, char* lds) {
;     ...
;       int rank[8];
;       u64 key[8];
; #pragma unroll
;       for (int e = 0; e < 8; ++e) { rank[e] = 0; key[e] = ((u64)__float_as_uint(v[e]) << 32) | (u64)(unsigned)(63 - (sub * 8 + e)); }
; #pragma unroll 1
;       for (int s2 = 1; s2 <= cur - 2; ++s2) {
;         const u64 k2 = ((u64)__float_as_uint(slab[q * 64 + s2]) << 32) | (u64)(unsigned)(63 - s2);
; #pragma unroll
;         for (int e = 0; e < 8; ++e) rank[e] += (k2 > key[e]) ? 1 : 0;
;       }
; #pragma unroll
;       for (int e = 0; e < 8; ++e) {
;         const int s = sub * 8 + e;
;         const bool forced = (s == 0) || (s == cur) || (s == cur - 1);
;         if (s <= cur && (forced || rank[e] < 13)) bits |= 1u << e;
;       }
;     }
.LBB0_906:
	s_or_b64 exec, exec, s[34:35]
	s_cmp_lt_u32 s6, 16
	s_mov_b64 s[0:1], -1
	s_waitcnt lgkmcnt(0)
	s_barrier
	s_cbranch_scc1 .LBB0_910
	v_sub_u32_e32 v51, 0, v75
	v_xor_b32_e32 v42, 63, v75
	v_mov_b32_e32 v43, v34
	v_mov_b32_e32 v54, 0
	s_mov_b32 s8, 62
	v_add_u32_e32 v34, 62, v51
	v_add_u32_e32 v44, 61, v51
	v_mov_b32_e32 v45, v36
	v_add_u32_e32 v36, 60, v51
	v_add_u32_e32 v46, 59, v51
	v_mov_b32_e32 v47, v38
	v_add_u32_e32 v38, 58, v51
	v_add_u32_e32 v48, 57, v51
	v_mov_b32_e32 v49, v40
	v_add_u32_e32 v40, 56, v51
	v_add_u32_e32 v59, 0x12004, v77
	v_mov_b32_e32 v58, 0
	v_mov_b32_e32 v57, 0
	v_mov_b32_e32 v56, 0
	v_mov_b32_e32 v55, 0
	v_mov_b32_e32 v53, 0
	v_mov_b32_e32 v52, 0
	v_mov_b32_e32 v51, 0
	ds_read_b32 v222, v59
.LBB0_908:
	s_waitcnt lgkmcnt(0)
	v_mov_b32_e32 v61, v222
	v_add_u32_e32 v59, 4, v59
	v_mov_b32_e32 v60, s8
	ds_read_b32 v222, v59
	s_add_i32 s8, s8, -1
	s_add_i32 s0, s6, s8
	s_cmp_eq_u32 s0, 64
	v_cmp_gt_u64_e64 s[0:1], v[60:61], v[42:43]
	s_nop 1
	v_addc_co_u32_e64 v54, s[0:1], 0, v54, s[0:1]
	v_cmp_gt_u64_e64 s[0:1], v[60:61], v[34:35]
	s_nop 1
	v_addc_co_u32_e64 v58, s[0:1], 0, v58, s[0:1]
	v_cmp_gt_u64_e64 s[0:1], v[60:61], v[44:45]
	s_nop 1
	v_addc_co_u32_e64 v57, s[0:1], 0, v57, s[0:1]
	v_cmp_gt_u64_e64 s[0:1], v[60:61], v[36:37]
	s_nop 1
	v_addc_co_u32_e64 v56, s[0:1], 0, v56, s[0:1]
	v_cmp_gt_u64_e64 s[0:1], v[60:61], v[46:47]
	s_nop 1
	v_addc_co_u32_e64 v55, s[0:1], 0, v55, s[0:1]
	v_cmp_gt_u64_e64 s[0:1], v[60:61], v[38:39]
	s_nop 1
	v_addc_co_u32_e64 v53, s[0:1], 0, v53, s[0:1]
	v_cmp_gt_u64_e64 s[0:1], v[60:61], v[48:49]
	s_nop 1
	v_addc_co_u32_e64 v52, s[0:1], 0, v52, s[0:1]
	v_cmp_gt_u64_e64 s[0:1], v[60:61], v[40:41]
	s_nop 1
	v_addc_co_u32_e64 v51, s[0:1], 0, v51, s[0:1]
	s_cbranch_scc0 .LBB0_908
	s_add_i32 s10, s6, -1
	v_cmp_eq_u32_e64 s[0:1], 0, v0
	v_cmp_eq_u32_e64 s[38:39], s6, v75
	v_cmp_eq_u32_e64 s[40:41], s10, v75
	s_or_b64 s[0:1], s[0:1], s[38:39]
	s_or_b64 s[8:9], s[0:1], s[40:41]
	v_cmp_gt_i32_e64 s[38:39], 13, v54
	v_cmp_ge_u32_e64 s[0:1], s6, v75
	s_or_b64 s[8:9], s[8:9], s[38:39]
	v_or_b32_e32 v34, 1, v75
	s_and_b64 s[0:1], s[0:1], s[8:9]
	v_cndmask_b32_e64 v35, 0, 1, s[0:1]
	v_cmp_eq_u32_e64 s[0:1], s6, v34
	v_cmp_eq_u32_e64 s[38:39], s10, v34
	s_or_b64 s[8:9], s[0:1], s[38:39]
	v_cmp_gt_i32_e64 s[0:1], 13, v58
	s_or_b64 s[0:1], s[8:9], s[0:1]
	s_and_b64 s[0:1], vcc, s[0:1]
	v_cndmask_b32_e64 v34, 0, 2, s[0:1]
	v_cmp_eq_u32_e32 vcc, s6, v76
	v_cmp_eq_u32_e64 s[0:1], s10, v76
	s_or_b64 s[8:9], vcc, s[0:1]
	v_cmp_gt_i32_e64 s[0:1], 13, v57
	v_cmp_ge_u32_e32 vcc, s6, v76
	s_or_b64 s[0:1], s[8:9], s[0:1]
	s_and_b64 s[0:1], vcc, s[0:1]
	v_or_b32_e32 v34, v34, v35
	v_cndmask_b32_e64 v35, 0, 4, s[0:1]
	v_cmp_eq_u32_e32 vcc, s6, v78
	v_cmp_eq_u32_e64 s[0:1], s10, v78
	s_or_b64 s[8:9], vcc, s[0:1]
	v_cmp_gt_i32_e64 s[0:1], 13, v56
	v_cmp_ge_u32_e32 vcc, s6, v78
	s_or_b64 s[0:1], s[8:9], s[0:1]
	s_and_b64 s[0:1], vcc, s[0:1]
	v_cndmask_b32_e64 v36, 0, 8, s[0:1]
	v_cmp_eq_u32_e32 vcc, s6, v85
	v_cmp_eq_u32_e64 s[0:1], s10, v85
	s_or_b64 s[8:9], vcc, s[0:1]
	v_cmp_gt_i32_e64 s[0:1], 13, v55
	v_cmp_ge_u32_e32 vcc, s6, v85
	s_or_b64 s[0:1], s[8:9], s[0:1]
	s_and_b64 s[0:1], vcc, s[0:1]
	v_or3_b32 v34, v34, v35, v36
	v_cndmask_b32_e64 v35, 0, 16, s[0:1]
	v_cmp_eq_u32_e32 vcc, s6, v86
	v_cmp_eq_u32_e64 s[0:1], s10, v86
	s_or_b64 s[8:9], vcc, s[0:1]
	v_cmp_gt_i32_e64 s[0:1], 13, v53
	v_cmp_ge_u32_e32 vcc, s6, v86
	s_or_b64 s[0:1], s[8:9], s[0:1]
	s_and_b64 s[0:1], vcc, s[0:1]
	v_cndmask_b32_e64 v36, 0, 32, s[0:1]
	v_cmp_eq_u32_e32 vcc, s6, v66
	v_cmp_eq_u32_e64 s[0:1], s10, v66
	s_or_b64 s[8:9], vcc, s[0:1]
	v_cmp_gt_i32_e64 s[0:1], 13, v52
	v_cmp_ge_u32_e32 vcc, s6, v66
	s_or_b64 s[0:1], s[8:9], s[0:1]
	s_and_b64 s[0:1], vcc, s[0:1]
	v_or3_b32 v34, v34, v35, v36
	v_cndmask_b32_e64 v35, 0, 64, s[0:1]
	v_cmp_eq_u32_e32 vcc, s6, v50
	v_cmp_eq_u32_e64 s[0:1], s10, v50
	s_or_b64 s[8:9], vcc, s[0:1]
	v_cmp_gt_i32_e64 s[0:1], 13, v51
	v_cmp_ge_u32_e32 vcc, s6, v50
	s_or_b64 s[0:1], s[8:9], s[0:1]
	s_and_b64 vcc, vcc, s[0:1]
	v_cndmask_b32_e32 v36, 0, v186, vcc
	v_or3_b32 v42, v34, v35, v36
	s_mov_b64 s[0:1], 0
